# opt51: opt50 with the static attention priority raise given to waves 0-3 instead of waves 4-7 (per-half A/B of the raise)
# baseline (speedup 1.0000x reference)
; __global__ void __launch_bounds__(512, 2) fwd_megakernel(Args a) {
;     ...
;     {
;         float lam;
;         { const float v1 = a.da_lambda[lane] * a.da_lambda[64 + lane], v2 = a.da_lambda[128 + lane] * a.da_lambda[192 + lane];
.LBB0_843:
	s_or_b64 exec, exec, s[0:1]
	v_readfirstlane_b32 s93, v246
	s_bitcmp0_b32 s93, 8
	s_cbranch_scc0 .Lprio_skip
	s_setprio 1
